# dynamic row scheduling (ticket counters) now in all four row phases ROW0..ROW3
# baseline (speedup 1.0000x reference)
.LBB0_324:
	v_lshrrev_b32_e32 v0, 6, v128
	v_lshl_add_u32 v4, s34, 3, v0
	v_lshlrev_b32_e32 v236, 8, v0
	v_add_u32_e32 v236, 0x480, v236
	s_lshl_b32 s82, s34, 3
	s_movk_i32 s0, 0x2400
	v_cmp_gt_i32_e32 vcc, s0, v4
	s_and_saveexec_b64 s[0:1], vcc
	s_cbranch_execz .LBB0_329
	v_mbcnt_lo_u32_b32 v1, -1, 0
	v_mbcnt_hi_u32_b32 v1, -1, v1
	s_waitcnt vmcnt(0)
	v_and_b32_e32 v2, 64, v1
	v_add_u32_e32 v2, 64, v2
	v_xor_b32_e32 v3, 1, v1
	v_cmp_lt_i32_e32 vcc, v3, v2
	v_lshlrev_b32_e32 v0, 2, v128
	s_lshl_b32 s2, s94, 3
	v_cndmask_b32_e32 v3, v1, v3, vcc
	v_lshlrev_b32_e32 v32, 2, v3
	v_xor_b32_e32 v3, 2, v1
	v_cmp_lt_i32_e32 vcc, v3, v2
	v_and_b32_e32 v0, 0xfc, v0
	s_add_u32 s4, s50, 0xc604000
	v_cndmask_b32_e32 v3, v1, v3, vcc
	v_lshlrev_b32_e32 v33, 2, v3
	v_xor_b32_e32 v3, 4, v1
	v_cmp_lt_i32_e32 vcc, v3, v2
	v_mov_b32_e32 v7, 0
	v_lshlrev_b32_e32 v6, 1, v0
	v_cndmask_b32_e32 v3, v1, v3, vcc
	v_lshlrev_b32_e32 v34, 2, v3
	v_xor_b32_e32 v3, 8, v1
	v_cmp_lt_i32_e32 vcc, v3, v2
	v_ashrrev_i32_e32 v5, 31, v4
	s_addc_u32 s5, s51, 0
	v_cndmask_b32_e32 v3, v1, v3, vcc
	v_lshlrev_b32_e32 v35, 2, v3
	v_xor_b32_e32 v3, 16, v1
	v_cmp_lt_i32_e32 vcc, v3, v2
	v_or_b32_e32 v26, 0x200, v0
	v_or_b32_e32 v28, 0x300, v0
	v_cndmask_b32_e32 v3, v1, v3, vcc
	v_lshlrev_b32_e32 v36, 2, v3
	v_xor_b32_e32 v3, 32, v1
	v_cmp_lt_i32_e32 vcc, v3, v2
	v_or_b32_e32 v2, 0x100, v0
	v_or_b32_e32 v16, 0x400, v0
	v_cndmask_b32_e32 v1, v1, v3, vcc
	v_or_b32_e32 v18, 0x500, v0
	v_or_b32_e32 v20, 0x600, v0
	v_or_b32_e32 v22, 0x700, v0
	v_lshl_add_u64 v[8:9], s[50:51], 0, v[6:7]
	s_mov_b64 s[8:9], 0xdb05000
	s_ashr_i32 s3, s2, 31
	v_lshlrev_b64 v[10:11], 13, v[4:5]
	v_lshlrev_b32_e32 v37, 2, v1
	v_lshl_add_u64 v[8:9], v[8:9], 0, s[8:9]
	v_lshl_add_u64 v[10:11], s[16:17], 0, v[10:11]
	s_lshl_b64 s[8:9], s[2:3], 13
	s_mov_b64 s[10:11], 0
	s_movk_i32 s26, 0x2000
	s_movk_i32 s27, 0x1fff
	s_mov_b32 s28, 0x12000
	v_mov_b64_e32 v[12:13], s[4:5]
	v_lshlrev_b32_e32 v14, 2, v0
	v_mov_b32_e32 v15, v7
	v_lshlrev_b32_e32 v16, 2, v16
	v_mov_b32_e32 v17, v7
	v_lshlrev_b32_e32 v18, 2, v18
	v_mov_b32_e32 v19, v7
	v_lshlrev_b32_e32 v20, 2, v20
	v_mov_b32_e32 v21, v7
	v_lshlrev_b32_e32 v22, 2, v22
	v_mov_b32_e32 v23, v7
	s_mov_b64 s[12:13], 0x2000
	v_lshlrev_b32_e32 v24, 2, v2
	v_mov_b32_e32 v25, v7
	v_lshlrev_b32_e32 v26, 2, v26
	v_mov_b32_e32 v27, v7
	v_lshlrev_b32_e32 v28, 2, v28
	v_mov_b32_e32 v29, v7
	v_mov_b32_e32 v38, 0x358637bd
	s_mov_b32 s29, 0x800000
	s_movk_i32 s30, 0x23ff
	s_branch .LBB0_327
.LBB0_326:
	s_or_b64 exec, exec, s[14:15]
	v_lshl_add_u64 v[2:3], v[0:1], 0, v[14:15]
	global_load_dwordx4 v[40:43], v[2:3], off
	global_load_dwordx4 v[44:47], v[2:3], off offset:1024
	global_load_dwordx4 v[48:51], v[2:3], off offset:2048
	global_load_dwordx4 v[52:55], v[2:3], off offset:3072
	v_lshl_add_u64 v[2:3], v[0:1], 0, v[16:17]
	v_lshl_add_u64 v[60:61], v[0:1], 0, v[18:19]
	global_load_dwordx4 v[56:59], v[2:3], off
	s_nop 0
	global_load_dwordx4 v[60:63], v[60:61], off
	v_lshl_add_u64 v[2:3], v[0:1], 0, v[20:21]
	v_lshl_add_u64 v[0:1], v[0:1], 0, v[22:23]
	global_load_dwordx4 v[64:67], v[2:3], off
	s_nop 0
	global_load_dwordx4 v[0:3], v[0:1], off
	v_lshrrev_b32_e32 v6, 3, v6
	v_ashrrev_i32_e32 v39, 12, v4
	v_add_u32_e32 v6, 2, v6
	v_cndmask_b32_e32 v6, v6, v39, vcc
	v_mad_i64_i32 v[124:125], s[4:5], v6, s28, v[12:13]
	v_lshl_add_u64 v[126:127], v[124:125], 0, s[12:13]
	v_lshl_add_u64 v[68:69], v[126:127], 0, v[14:15]
	v_lshl_add_u64 v[96:97], v[124:125], 0, v[14:15]
	v_lshl_add_u64 v[92:93], v[126:127], 0, v[24:25]
	v_lshl_add_u64 v[84:85], v[126:127], 0, v[26:27]
	v_lshl_add_u64 v[88:89], v[126:127], 0, v[28:29]
	global_load_dwordx4 v[68:71], v[68:69], off
	s_nop 0
	global_load_dwordx4 v[72:75], v[96:97], off
	global_load_dwordx4 v[76:79], v[96:97], off offset:1024
	global_load_dwordx4 v[80:83], v[96:97], off offset:2048
	s_nop 0
	global_load_dwordx4 v[84:87], v[84:85], off
	s_nop 0
	global_load_dwordx4 v[88:91], v[88:89], off
	s_nop 0
	global_load_dwordx4 v[92:95], v[92:93], off
	s_nop 0
	global_load_dwordx4 v[96:99], v[96:97], off offset:3072
	v_lshl_add_u64 v[100:101], v[126:127], 0, v[16:17]
	v_lshl_add_u64 v[104:105], v[124:125], 0, v[16:17]
	v_lshl_add_u64 v[108:109], v[126:127], 0, v[18:19]
	v_lshl_add_u64 v[112:113], v[124:125], 0, v[18:19]
	v_lshl_add_u64 v[116:117], v[126:127], 0, v[20:21]
	v_lshl_add_u64 v[120:121], v[124:125], 0, v[20:21]
	v_lshl_add_u64 v[126:127], v[126:127], 0, v[22:23]
	v_lshl_add_u64 v[130:131], v[124:125], 0, v[22:23]
	global_load_dwordx4 v[100:103], v[100:101], off
	s_nop 0
	global_load_dwordx4 v[104:107], v[104:105], off
	s_nop 0
	global_load_dwordx4 v[108:111], v[108:109], off
	s_nop 0
	global_load_dwordx4 v[112:115], v[112:113], off
	s_nop 0
	global_load_dwordx4 v[116:119], v[116:117], off
	s_nop 0
	global_load_dwordx4 v[120:123], v[120:121], off
	s_nop 0
	global_load_dwordx4 v[124:127], v[126:127], off
	s_nop 0
	global_load_dwordx4 v[130:133], v[130:131], off
	s_waitcnt vmcnt(23)
	v_mov_b32_e32 v136, v41
	s_waitcnt vmcnt(22)
	v_mov_b32_e32 v137, v45
	v_mov_b32_e32 v134, v40
	v_mov_b32_e32 v135, v44
	v_pk_mul_f32 v[136:137], v[136:137], v[136:137]
	v_mov_b32_e32 v138, v43
	v_mov_b32_e32 v139, v47
	v_pk_fma_f32 v[134:135], v[134:135], v[134:135], v[136:137]
	v_mov_b32_e32 v136, v42
	v_mov_b32_e32 v137, v46
	v_pk_mul_f32 v[138:139], v[138:139], v[138:139]
	s_waitcnt vmcnt(19)
	v_mul_f32_e32 v6, v56, v56
	v_pk_fma_f32 v[136:137], v[136:137], v[136:137], v[138:139]
	v_pk_mul_f32 v[138:139], v[48:49], v[48:49]
	v_pk_add_f32 v[134:135], v[134:135], v[136:137]
	v_pk_mul_f32 v[136:137], v[50:51], v[50:51]
	v_mul_f32_e32 v39, v57, v57
	v_pk_mov_b32 v[140:141], v[138:139], v[136:137] op_sel:[1,0]
	v_mov_b32_e32 v139, v137
	v_pk_add_f32 v[136:137], v[140:141], v[138:139]
	v_pk_add_f32 v[134:135], v[134:135], v[134:135] op_sel:[0,1] op_sel_hi:[1,0]
	v_pk_add_f32 v[136:137], v[136:137], v[136:137] op_sel:[0,1] op_sel_hi:[1,0]
	v_mov_b32_e32 v135, v6
	v_mov_b32_e32 v137, v39
	v_mul_f32_e32 v6, v53, v53
	v_pk_add_f32 v[134:135], v[134:135], v[136:137]
	v_pk_fma_f32 v[136:137], v[52:53], v[52:53], v[6:7] op_sel_hi:[1,1,0]
	v_mul_f32_e32 v6, v55, v55
	v_mul_f32_e32 v129, v58, v58
	v_mul_f32_e32 v140, v59, v59
	v_pk_fma_f32 v[138:139], v[54:55], v[54:55], v[6:7] op_sel_hi:[1,1,0]
	v_mov_b32_e32 v137, v129
	v_mov_b32_e32 v139, v140
	v_pk_add_f32 v[136:137], v[136:137], v[138:139]
	s_waitcnt vmcnt(18)
	v_pk_mul_f32 v[138:139], v[60:61], v[60:61]
	v_pk_add_f32 v[134:135], v[134:135], v[136:137]
	v_pk_mul_f32 v[136:137], v[62:63], v[62:63]
	s_waitcnt vmcnt(16)
	v_mul_f32_e32 v6, v0, v0
	v_pk_mov_b32 v[140:141], v[138:139], v[136:137] op_sel:[1,0]
	v_mov_b32_e32 v139, v137
	v_pk_add_f32 v[136:137], v[140:141], v[138:139]
	v_mul_f32_e32 v39, v1, v1
	v_pk_add_f32 v[134:135], v[134:135], v[134:135] op_sel:[0,1] op_sel_hi:[1,0]
	v_pk_add_f32 v[136:137], v[136:137], v[136:137] op_sel:[0,1] op_sel_hi:[1,0]
	v_mov_b32_e32 v135, v6
	v_mov_b32_e32 v137, v39
	v_mul_f32_e32 v6, v65, v65
	v_pk_add_f32 v[134:135], v[134:135], v[136:137]
	v_pk_fma_f32 v[136:137], v[64:65], v[64:65], v[6:7] op_sel_hi:[1,1,0]
	v_mul_f32_e32 v6, v67, v67
	v_mul_f32_e32 v129, v2, v2
	v_mul_f32_e32 v140, v3, v3
	v_pk_fma_f32 v[138:139], v[66:67], v[66:67], v[6:7] op_sel_hi:[1,1,0]
	v_mov_b32_e32 v137, v129
	v_mov_b32_e32 v139, v140
	v_pk_add_f32 v[136:137], v[136:137], v[138:139]
	v_lshlrev_b64 v[30:31], 12, v[30:31]
	v_pk_add_f32 v[134:135], v[134:135], v[136:137]
	v_lshl_add_u64 v[30:31], v[8:9], 0, v[30:31]
	v_add_f32_e32 v6, v134, v135
	ds_bpermute_b32 v39, v32, v6
	v_readfirstlane_b32 s83, v237
	s_add_u32 s83, s83, s94
	s_lshl_b32 s83, s83, 3
	s_sub_u32 s84, s83, s82
	s_mov_b32 s82, s83
	s_mov_b32 s85, 0
	s_mov_b64 s[2:3], s[84:85]
	s_lshl_b64 s[8:9], s[84:85], 13
	v_lshl_add_u64 v[4:5], v[4:5], 0, s[2:3]
	v_lshl_add_u64 v[10:11], v[10:11], 0, s[8:9]
	s_waitcnt lgkmcnt(0)
	v_add_f32_e32 v6, v6, v39
	ds_bpermute_b32 v39, v33, v6
	s_waitcnt lgkmcnt(0)
	v_add_f32_e32 v6, v6, v39
	ds_bpermute_b32 v39, v34, v6
	s_waitcnt lgkmcnt(0)
	v_add_f32_e32 v6, v6, v39
	ds_bpermute_b32 v39, v35, v6
	s_waitcnt lgkmcnt(0)
	v_add_f32_e32 v6, v6, v39
	ds_bpermute_b32 v39, v36, v6
	s_waitcnt lgkmcnt(0)
	v_add_f32_e32 v6, v6, v39
	ds_bpermute_b32 v39, v37, v6
	s_waitcnt lgkmcnt(0)
	v_add_f32_e32 v6, v6, v39
	v_fmamk_f32 v6, v6, 0x3a000000, v38
	v_mul_f32_e32 v39, 0x4b800000, v6
	v_cmp_gt_f32_e32 vcc, s29, v6
	s_nop 1
	v_cndmask_b32_e32 v6, v6, v39, vcc
	v_rsq_f32_e32 v6, v6
	s_nop 0
	v_mul_f32_e32 v39, 0x45800000, v6
	v_cndmask_b32_e32 v6, v6, v39, vcc
	v_pk_mul_f32 v[40:41], v[40:41], v[6:7] op_sel_hi:[1,0]
	v_pk_mul_f32 v[42:43], v[42:43], v[6:7] op_sel_hi:[1,0]
	s_waitcnt vmcnt(14)
	v_pk_fma_f32 v[40:41], v[68:69], v[40:41], v[72:73]
	v_pk_fma_f32 v[42:43], v[70:71], v[42:43], v[74:75]
	v_cvt_pk_bf16_f32 v40, v40, v41
	v_cvt_pk_bf16_f32 v41, v42, v43
	global_store_dwordx2 v[30:31], v[40:41], off
	v_pk_mul_f32 v[40:41], v[44:45], v[6:7] op_sel_hi:[1,0]
	v_pk_mul_f32 v[42:43], v[46:47], v[6:7] op_sel_hi:[1,0]
	s_waitcnt vmcnt(10)
	v_pk_fma_f32 v[40:41], v[92:93], v[40:41], v[76:77]
	v_pk_fma_f32 v[42:43], v[94:95], v[42:43], v[78:79]
	v_cvt_pk_bf16_f32 v40, v40, v41
	v_cvt_pk_bf16_f32 v41, v42, v43
	global_store_dwordx2 v[30:31], v[40:41], off offset:512
	v_pk_mul_f32 v[40:41], v[48:49], v[6:7] op_sel_hi:[1,0]
	v_pk_mul_f32 v[42:43], v[50:51], v[6:7] op_sel_hi:[1,0]
	v_pk_fma_f32 v[40:41], v[84:85], v[40:41], v[80:81]
	v_pk_fma_f32 v[42:43], v[86:87], v[42:43], v[82:83]
	v_cvt_pk_bf16_f32 v40, v40, v41
	v_cvt_pk_bf16_f32 v41, v42, v43
	global_store_dwordx2 v[30:31], v[40:41], off offset:1024
	v_pk_mul_f32 v[40:41], v[52:53], v[6:7] op_sel_hi:[1,0]
	v_pk_mul_f32 v[42:43], v[54:55], v[6:7] op_sel_hi:[1,0]
	s_waitcnt vmcnt(11)
	v_pk_fma_f32 v[40:41], v[88:89], v[40:41], v[96:97]
	v_pk_fma_f32 v[42:43], v[90:91], v[42:43], v[98:99]
	v_cvt_pk_bf16_f32 v40, v40, v41
	v_cvt_pk_bf16_f32 v41, v42, v43
	global_store_dwordx2 v[30:31], v[40:41], off offset:1536
	v_pk_mul_f32 v[40:41], v[56:57], v[6:7] op_sel_hi:[1,0]
	v_pk_mul_f32 v[42:43], v[58:59], v[6:7] op_sel_hi:[1,0]
	s_waitcnt vmcnt(10)
	v_pk_fma_f32 v[40:41], v[100:101], v[40:41], v[104:105]
	v_pk_fma_f32 v[42:43], v[102:103], v[42:43], v[106:107]
	v_cvt_pk_bf16_f32 v40, v40, v41
	v_cvt_pk_bf16_f32 v41, v42, v43
	global_store_dwordx2 v[30:31], v[40:41], off offset:2048
	v_pk_mul_f32 v[40:41], v[60:61], v[6:7] op_sel_hi:[1,0]
	v_pk_mul_f32 v[42:43], v[62:63], v[6:7] op_sel_hi:[1,0]
	s_waitcnt vmcnt(9)
	v_pk_fma_f32 v[40:41], v[108:109], v[40:41], v[112:113]
	v_pk_fma_f32 v[42:43], v[110:111], v[42:43], v[114:115]
	v_cvt_pk_bf16_f32 v40, v40, v41
	v_cvt_pk_bf16_f32 v41, v42, v43
	global_store_dwordx2 v[30:31], v[40:41], off offset:2560
	v_pk_mul_f32 v[40:41], v[64:65], v[6:7] op_sel_hi:[1,0]
	v_pk_mul_f32 v[42:43], v[66:67], v[6:7] op_sel_hi:[1,0]
	v_pk_mul_f32 v[0:1], v[0:1], v[6:7] op_sel_hi:[1,0]
	v_pk_mul_f32 v[2:3], v[2:3], v[6:7] op_sel_hi:[1,0]
	s_waitcnt vmcnt(8)
	v_pk_fma_f32 v[42:43], v[118:119], v[42:43], v[122:123]
	v_pk_fma_f32 v[40:41], v[116:117], v[40:41], v[120:121]
	s_waitcnt vmcnt(6)
	v_pk_fma_f32 v[2:3], v[126:127], v[2:3], v[132:133]
	v_pk_fma_f32 v[0:1], v[124:125], v[0:1], v[130:131]
	v_cmp_lt_i32_e32 vcc, s30, v4
	v_cvt_pk_bf16_f32 v40, v40, v41
	v_cvt_pk_bf16_f32 v41, v42, v43
	v_cvt_pk_bf16_f32 v0, v0, v1
	v_cvt_pk_bf16_f32 v1, v2, v3
	s_or_b64 s[10:11], vcc, s[10:11]
	global_store_dwordx2 v[30:31], v[40:41], off offset:3072
	global_store_dwordx2 v[30:31], v[0:1], off offset:3584
	s_andn2_b64 exec, exec, s[10:11]
	s_cbranch_execz .LBB0_329
.LBB0_327:
	s_mov_b64 s[80:81], exec
	s_mov_b64 exec, 1
	v_mov_b32_e32 v237, 1
	global_atomic_add v237, v236, v237, s[50:51] sc0
	s_mov_b64 exec, s[80:81]
	v_cmp_gt_i32_e32 vcc, s26, v4
	v_cmp_lt_i32_e64 s[4:5], s27, v4
	v_add_u32_e32 v6, 0xffffe000, v4
	v_mov_b64_e32 v[30:31], v[4:5]
	v_mov_b64_e32 v[0:1], v[10:11]
	s_and_saveexec_b64 s[14:15], s[4:5]
	s_cbranch_execz .LBB0_326
	v_lshlrev_b64 v[0:1], 13, v[6:7]
	v_lshl_add_u64 v[0:1], s[18:19], 0, v[0:1]
	v_mov_b32_e32 v30, v4
	v_mov_b32_e32 v31, v7
	s_branch .LBB0_326

.LBB0_735:
	v_lshrrev_b32_e32 v0, 6, v128
	s_waitcnt vmcnt(0)
	v_lshl_add_u32 v130, s34, 3, v0
	v_lshlrev_b32_e32 v236, 8, v0
	v_add_u32_e32 v236, 0xc80, v236
	s_lshl_b32 s82, s34, 3
	s_movk_i32 s0, 0x2400
	v_cmp_gt_i32_e32 vcc, s0, v130
	s_and_saveexec_b64 s[0:1], vcc
	s_cbranch_execz .LBB0_742
	v_lshlrev_b32_e32 v0, 2, v128
	v_and_b32_e32 v132, 0xfc, v0
	v_mbcnt_lo_u32_b32 v0, -1, 0
	v_mbcnt_hi_u32_b32 v0, -1, v0
	v_and_b32_e32 v1, 64, v0
	v_add_u32_e32 v1, 64, v1
	v_xor_b32_e32 v2, 1, v0
	v_cmp_lt_i32_e32 vcc, v2, v1
	s_lshl_b32 s6, s94, 3
	s_add_u32 s8, s50, 0xc604000
	v_cndmask_b32_e32 v2, v0, v2, vcc
	v_lshlrev_b32_e32 v129, 2, v2
	v_xor_b32_e32 v2, 2, v0
	v_cmp_lt_i32_e32 vcc, v2, v1
	s_addc_u32 s9, s51, 0
	s_add_u32 s10, s50, 0xff05000
	v_cndmask_b32_e32 v2, v0, v2, vcc
	v_lshlrev_b32_e32 v133, 2, v2
	v_xor_b32_e32 v2, 4, v0
	v_cmp_lt_i32_e32 vcc, v2, v1
	s_addc_u32 s11, s51, 0
	s_add_u32 s12, s50, 0x1aa05000
	v_cndmask_b32_e32 v2, v0, v2, vcc
	v_lshlrev_b32_e32 v137, 2, v2
	v_xor_b32_e32 v2, 8, v0
	v_cmp_lt_i32_e32 vcc, v2, v1
	s_addc_u32 s13, s51, 0
	s_add_u32 s14, s50, 0x12305000
	v_cndmask_b32_e32 v2, v0, v2, vcc
	v_lshlrev_b32_e32 v139, 2, v2
	v_xor_b32_e32 v2, 16, v0
	v_cmp_lt_i32_e32 vcc, v2, v1
	s_addc_u32 s15, s51, 0
	s_add_u32 s26, s50, 0x1ce05000
	v_cndmask_b32_e32 v2, v0, v2, vcc
	v_lshlrev_b32_e32 v141, 2, v2
	v_xor_b32_e32 v2, 32, v0
	v_cmp_lt_i32_e32 vcc, v2, v1
	v_mov_b32_e32 v135, 0
	v_lshlrev_b32_e32 v134, 1, v132
	v_cndmask_b32_e32 v0, v0, v2, vcc
	s_addc_u32 s27, s51, 0
	v_lshlrev_b32_e32 v143, 2, v0
	v_lshl_add_u64 v[0:1], s[50:51], 0, v[134:135]
	s_mov_b64 s[4:5], 0xdb05000
	v_ashrrev_i32_e32 v131, 31, v130
	s_ashr_i32 s7, s6, 31
	v_or_b32_e32 v136, 0x100, v132
	v_or_b32_e32 v138, 0x200, v132
	v_or_b32_e32 v140, 0x300, v132
	v_or_b32_e32 v142, 0x400, v132
	v_or_b32_e32 v144, 0x500, v132
	v_or_b32_e32 v146, 0x600, v132
	v_or_b32_e32 v148, 0x700, v132
	v_lshl_add_u64 v[150:151], v[0:1], 0, s[4:5]
	v_lshlrev_b64 v[152:153], 13, v[130:131]
	s_lshl_b64 s[28:29], s[6:7], 13
	s_mov_b64 s[30:31], 0
	s_movk_i32 s33, 0x2000
	s_movk_i32 s35, 0x1fff
	s_mov_b32 s58, 0x12000
	s_mov_b64 s[52:53], 0x4000
	s_mov_b64 s[54:55], 0x8000
	s_mov_b64 s[56:57], 0x6000
	v_mov_b32_e32 v145, 0x358637bd
	s_mov_b32 s59, 0x800000
	s_movk_i32 s60, 0x23ff
	s_branch .LBB0_738
.LBB0_737:
	s_or_b64 exec, exec, s[4:5]
	v_lshrrev_b32_e32 v32, 3, v134
	v_lshlrev_b32_e32 v134, 2, v132
	v_lshl_add_u64 v[2:3], v[0:1], 0, v[134:135]
	v_lshlrev_b32_e32 v162, 2, v142
	v_mov_b32_e32 v163, v135
	global_load_dwordx4 v[24:27], v[2:3], off
	global_load_dwordx4 v[20:23], v[2:3], off offset:1024
	global_load_dwordx4 v[16:19], v[2:3], off offset:2048
	global_load_dwordx4 v[12:15], v[2:3], off offset:3072
	v_lshl_add_u64 v[2:3], v[0:1], 0, v[162:163]
	v_lshlrev_b32_e32 v160, 2, v144
	v_mov_b32_e32 v161, v135
	v_lshlrev_b32_e32 v158, 2, v146
	v_mov_b32_e32 v159, v135
	v_lshlrev_b32_e32 v156, 2, v148
	v_mov_b32_e32 v157, v135
	v_lshl_add_u64 v[4:5], v[0:1], 0, v[160:161]
	global_load_dwordx4 v[28:31], v[2:3], off
	global_load_dwordx4 v[8:11], v[4:5], off
	v_lshl_add_u64 v[2:3], v[0:1], 0, v[158:159]
	v_lshl_add_u64 v[0:1], v[0:1], 0, v[156:157]
	global_load_dwordx4 v[4:7], v[2:3], off
	s_nop 0
	global_load_dwordx4 v[0:3], v[0:1], off
	v_ashrrev_i32_e32 v33, 12, v130
	v_add_u32_e32 v32, 2, v32
	v_cndmask_b32_e32 v34, v32, v33, vcc
	v_mov_b64_e32 v[32:33], s[8:9]
	v_mad_i64_i32 v[64:65], s[4:5], v34, s58, v[32:33]
	v_lshlrev_b64 v[56:57], 11, v[154:155]
	v_or_b32_e32 v32, v56, v132
	v_mov_b32_e32 v33, v57
	v_lshlrev_b64 v[32:33], 1, v[32:33]
	v_lshl_add_u64 v[34:35], s[10:11], 0, v[32:33]
	v_lshl_add_u64 v[36:37], s[14:15], 0, v[32:33]
	v_lshl_add_u64 v[38:39], s[12:13], 0, v[32:33]
	v_lshl_add_u64 v[32:33], s[26:27], 0, v[32:33]
	global_load_dwordx2 v[100:101], v[34:35], off
	global_load_dwordx2 v[102:103], v[36:37], off
	global_load_dwordx2 v[104:105], v[38:39], off
	global_load_dwordx2 v[106:107], v[32:33], off
	v_or_b32_e32 v34, v56, v136
	v_mov_b32_e32 v35, v57
	v_lshl_add_u64 v[58:59], v[64:65], 0, s[52:53]
	v_lshlrev_b64 v[36:37], 1, v[34:35]
	v_lshl_add_u64 v[32:33], v[58:59], 0, v[134:135]
	v_lshl_add_u64 v[38:39], s[10:11], 0, v[36:37]
	global_load_dwordx4 v[32:35], v[32:33], off
	s_nop 0
	global_load_dwordx2 v[108:109], v[38:39], off
	v_lshl_add_u64 v[38:39], s[14:15], 0, v[36:37]
	v_lshl_add_u64 v[40:41], s[12:13], 0, v[36:37]
	v_lshl_add_u64 v[36:37], s[26:27], 0, v[36:37]
	global_load_dwordx2 v[110:111], v[38:39], off
	global_load_dwordx2 v[112:113], v[40:41], off
	global_load_dwordx2 v[114:115], v[36:37], off
	v_or_b32_e32 v38, v56, v138
	v_mov_b32_e32 v39, v57
	v_lshlrev_b32_e32 v66, 2, v136
	v_mov_b32_e32 v67, v135
	v_lshlrev_b64 v[40:41], 1, v[38:39]
	v_lshl_add_u64 v[36:37], v[58:59], 0, v[66:67]
	v_lshl_add_u64 v[42:43], s[10:11], 0, v[40:41]
	global_load_dwordx4 v[36:39], v[36:37], off
	s_nop 0
	global_load_dwordx2 v[116:117], v[42:43], off
	v_lshl_add_u64 v[42:43], s[14:15], 0, v[40:41]
	v_lshl_add_u64 v[44:45], s[12:13], 0, v[40:41]
	v_lshl_add_u64 v[40:41], s[26:27], 0, v[40:41]
	global_load_dwordx2 v[118:119], v[42:43], off
	global_load_dwordx2 v[120:121], v[44:45], off
	global_load_dwordx2 v[122:123], v[40:41], off
	v_or_b32_e32 v42, v56, v140
	v_mov_b32_e32 v43, v57
	v_lshlrev_b32_e32 v68, 2, v138
	v_mov_b32_e32 v69, v135
	v_lshlrev_b64 v[44:45], 1, v[42:43]
	v_lshl_add_u64 v[40:41], v[58:59], 0, v[68:69]
	v_lshl_add_u64 v[46:47], s[10:11], 0, v[44:45]
	global_load_dwordx4 v[40:43], v[40:41], off
	s_nop 0
	global_load_dwordx2 v[124:125], v[46:47], off
	v_lshl_add_u64 v[46:47], s[14:15], 0, v[44:45]
	v_lshl_add_u64 v[48:49], s[12:13], 0, v[44:45]
	v_lshl_add_u64 v[44:45], s[26:27], 0, v[44:45]
	global_load_dwordx2 v[126:127], v[46:47], off
	global_load_dwordx2 v[180:181], v[48:49], off
	global_load_dwordx2 v[182:183], v[44:45], off
	v_or_b32_e32 v46, v56, v142
	v_mov_b32_e32 v47, v57
	v_lshlrev_b32_e32 v70, 2, v140
	v_mov_b32_e32 v71, v135
	v_lshlrev_b64 v[48:49], 1, v[46:47]
	v_lshl_add_u64 v[44:45], v[58:59], 0, v[70:71]
	v_lshl_add_u64 v[50:51], s[10:11], 0, v[48:49]
	global_load_dwordx4 v[44:47], v[44:45], off
	s_nop 0
	global_load_dwordx2 v[184:185], v[50:51], off
	v_lshl_add_u64 v[50:51], s[14:15], 0, v[48:49]
	v_lshl_add_u64 v[52:53], s[12:13], 0, v[48:49]
	v_lshl_add_u64 v[48:49], s[26:27], 0, v[48:49]
	global_load_dwordx2 v[186:187], v[50:51], off
	global_load_dwordx2 v[98:99], v[52:53], off
	global_load_dwordx2 v[96:97], v[48:49], off
	v_or_b32_e32 v50, v56, v144
	v_mov_b32_e32 v51, v57
	v_lshlrev_b64 v[52:53], 1, v[50:51]
	v_lshl_add_u64 v[48:49], v[58:59], 0, v[162:163]
	v_lshl_add_u64 v[54:55], s[10:11], 0, v[52:53]
	global_load_dwordx4 v[48:51], v[48:49], off
	s_nop 0
	global_load_dwordx2 v[92:93], v[54:55], off
	v_lshl_add_u64 v[54:55], s[14:15], 0, v[52:53]
	v_lshl_add_u64 v[60:61], s[12:13], 0, v[52:53]
	v_lshl_add_u64 v[52:53], s[26:27], 0, v[52:53]
	global_load_dwordx2 v[94:95], v[54:55], off
	global_load_dwordx2 v[90:91], v[60:61], off
	global_load_dwordx2 v[88:89], v[52:53], off
	v_or_b32_e32 v54, v56, v146
	v_mov_b32_e32 v55, v57
	v_lshlrev_b64 v[60:61], 1, v[54:55]
	v_lshl_add_u64 v[52:53], v[58:59], 0, v[160:161]
	v_lshl_add_u64 v[62:63], s[10:11], 0, v[60:61]
	v_or_b32_e32 v56, v56, v148
	global_load_dwordx4 v[52:55], v[52:53], off
	s_nop 0
	global_load_dwordx2 v[84:85], v[62:63], off
	v_lshl_add_u64 v[62:63], s[14:15], 0, v[60:61]
	v_lshl_add_u64 v[72:73], s[12:13], 0, v[60:61]
	v_lshl_add_u64 v[60:61], s[26:27], 0, v[60:61]
	v_lshlrev_b64 v[56:57], 1, v[56:57]
	global_load_dwordx2 v[86:87], v[62:63], off
	global_load_dwordx2 v[82:83], v[72:73], off
	global_load_dwordx2 v[80:81], v[60:61], off
	v_lshl_add_u64 v[60:61], v[58:59], 0, v[158:159]
	v_lshl_add_u64 v[72:73], s[10:11], 0, v[56:57]
	global_load_dwordx4 v[60:63], v[60:61], off
	s_nop 0
	global_load_dwordx2 v[76:77], v[72:73], off
	v_lshl_add_u64 v[72:73], s[14:15], 0, v[56:57]
	v_lshl_add_u64 v[74:75], s[12:13], 0, v[56:57]
	v_lshl_add_u64 v[56:57], s[26:27], 0, v[56:57]
	global_load_dwordx2 v[78:79], v[72:73], off
	s_nop 0
	global_load_dwordx2 v[74:75], v[74:75], off
	s_nop 0
	global_load_dwordx2 v[72:73], v[56:57], off
	v_lshl_add_u64 v[56:57], v[58:59], 0, v[156:157]
	global_load_dwordx4 v[56:59], v[56:57], off
	s_waitcnt vmcnt(39)
	v_lshlrev_b32_e32 v166, 16, v100
	v_and_b32_e32 v167, 0xffff0000, v100
	s_waitcnt vmcnt(38)
	v_lshlrev_b32_e32 v168, 16, v102
	v_and_b32_e32 v169, 0xffff0000, v102
	v_lshlrev_b32_e32 v100, 16, v101
	v_and_b32_e32 v101, 0xffff0000, v101
	v_lshlrev_b32_e32 v102, 16, v103
	v_and_b32_e32 v103, 0xffff0000, v103
	v_pk_add_f32 v[166:167], v[166:167], v[168:169]
	s_waitcnt vmcnt(37)
	v_lshlrev_b32_e32 v168, 16, v104
	v_and_b32_e32 v169, 0xffff0000, v104
	s_waitcnt vmcnt(36)
	v_lshlrev_b32_e32 v170, 16, v106
	v_and_b32_e32 v171, 0xffff0000, v106
	v_pk_add_f32 v[100:101], v[100:101], v[102:103]
	v_lshlrev_b32_e32 v102, 16, v105
	v_and_b32_e32 v103, 0xffff0000, v105
	v_lshlrev_b32_e32 v104, 16, v107
	v_and_b32_e32 v105, 0xffff0000, v107
	v_pk_add_f32 v[168:169], v[168:169], v[170:171]
	v_pk_add_f32 v[102:103], v[102:103], v[104:105]
	v_pk_add_f32 v[166:167], v[166:167], v[168:169]
	v_pk_add_f32 v[168:169], v[100:101], v[102:103]
	s_waitcnt vmcnt(34)
	v_lshlrev_b32_e32 v100, 16, v108
	v_and_b32_e32 v101, 0xffff0000, v108
	s_waitcnt vmcnt(33)
	v_lshlrev_b32_e32 v102, 16, v110
	v_and_b32_e32 v103, 0xffff0000, v110
	v_pk_add_f32 v[100:101], v[100:101], v[102:103]
	s_waitcnt vmcnt(32)
	v_lshlrev_b32_e32 v102, 16, v112
	v_and_b32_e32 v103, 0xffff0000, v112
	s_waitcnt vmcnt(31)
	v_lshlrev_b32_e32 v104, 16, v114
	v_and_b32_e32 v105, 0xffff0000, v114
	v_pk_add_f32 v[102:103], v[102:103], v[104:105]
	v_lshlrev_b32_e32 v104, 16, v115
	v_pk_add_f32 v[170:171], v[100:101], v[102:103]
	v_lshlrev_b32_e32 v100, 16, v109
	v_and_b32_e32 v101, 0xffff0000, v109
	v_lshlrev_b32_e32 v102, 16, v111
	v_and_b32_e32 v103, 0xffff0000, v111
	v_pk_add_f32 v[100:101], v[100:101], v[102:103]
	v_lshlrev_b32_e32 v102, 16, v113
	v_and_b32_e32 v103, 0xffff0000, v113
	v_and_b32_e32 v105, 0xffff0000, v115
	v_pk_add_f32 v[102:103], v[102:103], v[104:105]
	s_waitcnt vmcnt(26)
	v_lshlrev_b32_e32 v104, 16, v122
	v_pk_add_f32 v[172:173], v[100:101], v[102:103]
	v_lshlrev_b32_e32 v100, 16, v116
	v_and_b32_e32 v101, 0xffff0000, v116
	v_lshlrev_b32_e32 v102, 16, v118
	v_and_b32_e32 v103, 0xffff0000, v118
	v_pk_add_f32 v[100:101], v[100:101], v[102:103]
	v_lshlrev_b32_e32 v102, 16, v120
	v_and_b32_e32 v103, 0xffff0000, v120
	v_and_b32_e32 v105, 0xffff0000, v122
	v_pk_add_f32 v[102:103], v[102:103], v[104:105]
	v_lshlrev_b32_e32 v104, 16, v123
	v_pk_add_f32 v[174:175], v[100:101], v[102:103]
	v_lshlrev_b32_e32 v100, 16, v117
	v_and_b32_e32 v101, 0xffff0000, v117
	v_lshlrev_b32_e32 v102, 16, v119
	v_and_b32_e32 v103, 0xffff0000, v119
	v_pk_add_f32 v[100:101], v[100:101], v[102:103]
	v_lshlrev_b32_e32 v102, 16, v121
	v_and_b32_e32 v103, 0xffff0000, v121
	v_and_b32_e32 v105, 0xffff0000, v123
	v_pk_add_f32 v[102:103], v[102:103], v[104:105]
	s_waitcnt vmcnt(21)
	v_lshlrev_b32_e32 v104, 16, v182
	v_pk_add_f32 v[176:177], v[100:101], v[102:103]
	v_mov_b32_e32 v102, v175
	v_mov_b32_e32 v103, v177
	v_mov_b32_e32 v100, v174
	v_mov_b32_e32 v101, v176
	v_pk_mul_f32 v[102:103], v[102:103], v[102:103]
	v_and_b32_e32 v105, 0xffff0000, v182
	v_pk_fma_f32 v[100:101], v[100:101], v[100:101], v[102:103]
	v_lshlrev_b32_e32 v102, 16, v126
	v_pk_add_f32 v[192:193], v[100:101], v[100:101] op_sel:[0,1] op_sel_hi:[1,0]
	v_lshlrev_b32_e32 v100, 16, v124
	v_and_b32_e32 v101, 0xffff0000, v124
	v_and_b32_e32 v103, 0xffff0000, v126
	v_pk_add_f32 v[100:101], v[100:101], v[102:103]
	v_lshlrev_b32_e32 v102, 16, v180
	v_and_b32_e32 v103, 0xffff0000, v180
	v_pk_add_f32 v[102:103], v[102:103], v[104:105]
	v_lshlrev_b32_e32 v104, 16, v183
	v_pk_add_f32 v[178:179], v[100:101], v[102:103]
	v_lshlrev_b32_e32 v100, 16, v125
	v_and_b32_e32 v101, 0xffff0000, v125
	v_lshlrev_b32_e32 v102, 16, v127
	v_and_b32_e32 v103, 0xffff0000, v127
	v_pk_add_f32 v[100:101], v[100:101], v[102:103]
	v_lshlrev_b32_e32 v102, 16, v181
	v_and_b32_e32 v103, 0xffff0000, v181
	v_and_b32_e32 v105, 0xffff0000, v183
	v_pk_add_f32 v[102:103], v[102:103], v[104:105]
	s_waitcnt vmcnt(16)
	v_lshlrev_b32_e32 v104, 16, v96
	v_pk_add_f32 v[180:181], v[100:101], v[102:103]
	v_mul_f32_e32 v100, v179, v179
	v_pk_fma_f32 v[198:199], v[178:179], v[178:179], v[100:101] op_sel_hi:[1,1,0]
	v_mul_f32_e32 v100, v181, v181
	v_pk_fma_f32 v[200:201], v[180:181], v[180:181], v[100:101] op_sel_hi:[1,1,0]
	v_lshlrev_b32_e32 v100, 16, v184
	v_and_b32_e32 v101, 0xffff0000, v184
	v_lshlrev_b32_e32 v102, 16, v186
	v_and_b32_e32 v103, 0xffff0000, v186
	v_pk_add_f32 v[100:101], v[100:101], v[102:103]
	v_lshlrev_b32_e32 v102, 16, v98
	v_and_b32_e32 v103, 0xffff0000, v98
	v_and_b32_e32 v105, 0xffff0000, v96
	v_pk_add_f32 v[102:103], v[102:103], v[104:105]
	v_lshlrev_b32_e32 v98, 16, v99
	v_pk_add_f32 v[182:183], v[100:101], v[102:103]
	v_lshlrev_b32_e32 v100, 16, v185
	v_and_b32_e32 v101, 0xffff0000, v185
	v_lshlrev_b32_e32 v102, 16, v187
	v_and_b32_e32 v103, 0xffff0000, v187
	v_and_b32_e32 v99, 0xffff0000, v99
	v_lshlrev_b32_e32 v96, 16, v97
	v_and_b32_e32 v97, 0xffff0000, v97
	v_pk_add_f32 v[100:101], v[100:101], v[102:103]
	v_pk_add_f32 v[96:97], v[98:99], v[96:97]
	s_waitcnt vmcnt(13)
	v_lshlrev_b32_e32 v98, 16, v94
	v_pk_add_f32 v[184:185], v[100:101], v[96:97]
	v_lshlrev_b32_e32 v96, 16, v92
	v_and_b32_e32 v97, 0xffff0000, v92
	v_and_b32_e32 v99, 0xffff0000, v94
	v_pk_add_f32 v[96:97], v[96:97], v[98:99]
	s_waitcnt vmcnt(12)
	v_lshlrev_b32_e32 v98, 16, v90
	v_and_b32_e32 v99, 0xffff0000, v90
	s_waitcnt vmcnt(11)
	v_lshlrev_b32_e32 v100, 16, v88
	v_and_b32_e32 v101, 0xffff0000, v88
	v_lshlrev_b32_e32 v92, 16, v93
	v_and_b32_e32 v93, 0xffff0000, v93
	v_lshlrev_b32_e32 v94, 16, v95
	v_and_b32_e32 v95, 0xffff0000, v95
	v_lshlrev_b32_e32 v90, 16, v91
	v_and_b32_e32 v91, 0xffff0000, v91
	v_lshlrev_b32_e32 v88, 16, v89
	v_and_b32_e32 v89, 0xffff0000, v89
	v_pk_add_f32 v[98:99], v[98:99], v[100:101]
	v_pk_add_f32 v[92:93], v[92:93], v[94:95]
	v_pk_add_f32 v[88:89], v[90:91], v[88:89]
	v_pk_add_f32 v[186:187], v[96:97], v[98:99]
	v_pk_add_f32 v[188:189], v[92:93], v[88:89]
	v_mov_b32_e32 v90, v187
	v_mov_b32_e32 v91, v189
	v_mov_b32_e32 v88, v186
	v_mov_b32_e32 v89, v188
	v_pk_mul_f32 v[90:91], v[90:91], v[90:91]
	s_waitcnt vmcnt(6)
	v_lshlrev_b32_e32 v92, 16, v80
	v_pk_fma_f32 v[88:89], v[88:89], v[88:89], v[90:91]
	v_lshlrev_b32_e32 v90, 16, v86
	v_pk_add_f32 v[206:207], v[88:89], v[88:89] op_sel:[0,1] op_sel_hi:[1,0]
	v_lshlrev_b32_e32 v88, 16, v84
	v_and_b32_e32 v89, 0xffff0000, v84
	v_and_b32_e32 v91, 0xffff0000, v86
	v_pk_add_f32 v[88:89], v[88:89], v[90:91]
	v_lshlrev_b32_e32 v90, 16, v82
	v_and_b32_e32 v91, 0xffff0000, v82
	v_and_b32_e32 v93, 0xffff0000, v80
	v_pk_add_f32 v[90:91], v[90:91], v[92:93]
	v_lshlrev_b32_e32 v84, 16, v85
	v_and_b32_e32 v85, 0xffff0000, v85
	v_lshlrev_b32_e32 v86, 16, v87
	v_and_b32_e32 v87, 0xffff0000, v87
	v_lshlrev_b32_e32 v82, 16, v83
	v_and_b32_e32 v83, 0xffff0000, v83
	v_lshlrev_b32_e32 v80, 16, v81
	v_and_b32_e32 v81, 0xffff0000, v81
	v_pk_add_f32 v[190:191], v[88:89], v[90:91]
	v_pk_add_f32 v[84:85], v[84:85], v[86:87]
	v_pk_add_f32 v[80:81], v[82:83], v[80:81]
	s_waitcnt vmcnt(3)
	v_lshlrev_b32_e32 v82, 16, v78
	v_pk_add_f32 v[194:195], v[84:85], v[80:81]
	v_mul_f32_e32 v80, v191, v191
	v_pk_fma_f32 v[208:209], v[190:191], v[190:191], v[80:81] op_sel_hi:[1,1,0]
	v_mul_f32_e32 v80, v195, v195
	v_pk_fma_f32 v[210:211], v[194:195], v[194:195], v[80:81] op_sel_hi:[1,1,0]
	v_lshlrev_b32_e32 v80, 16, v76
	v_and_b32_e32 v81, 0xffff0000, v76
	v_and_b32_e32 v83, 0xffff0000, v78
	v_pk_add_f32 v[80:81], v[80:81], v[82:83]
	s_waitcnt vmcnt(2)
	v_lshlrev_b32_e32 v82, 16, v74
	v_and_b32_e32 v83, 0xffff0000, v74
	s_waitcnt vmcnt(1)
	v_lshlrev_b32_e32 v84, 16, v72
	v_and_b32_e32 v85, 0xffff0000, v72
	v_lshlrev_b32_e32 v76, 16, v77
	v_and_b32_e32 v77, 0xffff0000, v77
	v_lshlrev_b32_e32 v78, 16, v79
	v_and_b32_e32 v79, 0xffff0000, v79
	v_lshlrev_b32_e32 v74, 16, v75
	v_and_b32_e32 v75, 0xffff0000, v75
	v_lshlrev_b32_e32 v72, 16, v73
	v_and_b32_e32 v73, 0xffff0000, v73
	v_pk_add_f32 v[82:83], v[82:83], v[84:85]
	v_pk_add_f32 v[76:77], v[76:77], v[78:79]
	v_pk_add_f32 v[72:73], v[74:75], v[72:73]
	v_pk_add_f32 v[196:197], v[80:81], v[82:83]
	v_pk_add_f32 v[212:213], v[76:77], v[72:73]
	v_pk_mul_f32 v[202:203], v[182:183], v[182:183]
	v_pk_mul_f32 v[204:205], v[184:185], v[184:185]
	v_pk_mul_f32 v[214:215], v[196:197], v[196:197]
	v_pk_mul_f32 v[216:217], v[212:213], v[212:213]
	v_lshl_add_u64 v[218:219], v[64:65], 0, s[54:55]
	v_lshl_add_u64 v[64:65], v[64:65], 0, s[56:57]
	v_lshl_add_u64 v[72:73], v[218:219], 0, v[134:135]
	v_lshl_add_u64 v[74:75], v[64:65], 0, v[134:135]
	global_load_dwordx4 v[120:123], v[72:73], off
	global_load_dwordx4 v[124:127], v[74:75], off
	v_lshl_add_u64 v[72:73], v[218:219], 0, v[66:67]
	v_lshl_add_u64 v[66:67], v[64:65], 0, v[66:67]
	global_load_dwordx4 v[112:115], v[72:73], off
	global_load_dwordx4 v[116:119], v[66:67], off
	v_lshl_add_u64 v[66:67], v[218:219], 0, v[68:69]
	v_lshl_add_u64 v[68:69], v[64:65], 0, v[68:69]
	global_load_dwordx4 v[104:107], v[66:67], off
	global_load_dwordx4 v[108:111], v[68:69], off
	v_lshl_add_u64 v[66:67], v[218:219], 0, v[70:71]
	v_lshl_add_u64 v[68:69], v[64:65], 0, v[70:71]
	global_load_dwordx4 v[96:99], v[66:67], off
	global_load_dwordx4 v[100:103], v[68:69], off
	v_lshl_add_u64 v[66:67], v[218:219], 0, v[162:163]
	v_lshl_add_u64 v[68:69], v[64:65], 0, v[162:163]
	global_load_dwordx4 v[88:91], v[66:67], off
	global_load_dwordx4 v[92:95], v[68:69], off
	v_lshl_add_u64 v[66:67], v[218:219], 0, v[160:161]
	v_lshl_add_u64 v[68:69], v[64:65], 0, v[160:161]
	global_load_dwordx4 v[80:83], v[66:67], off
	global_load_dwordx4 v[84:87], v[68:69], off
	v_lshl_add_u64 v[66:67], v[218:219], 0, v[158:159]
	v_lshl_add_u64 v[68:69], v[64:65], 0, v[158:159]
	global_load_dwordx4 v[72:75], v[66:67], off
	global_load_dwordx4 v[76:79], v[68:69], off
	v_lshl_add_u64 v[66:67], v[218:219], 0, v[156:157]
	v_lshl_add_u64 v[68:69], v[64:65], 0, v[156:157]
	global_load_dwordx4 v[64:67], v[66:67], off
	s_nop 0
	global_load_dwordx4 v[68:71], v[68:69], off
	v_mov_b32_e32 v222, v169
	v_mov_b32_e32 v223, v173
	v_mov_b32_e32 v218, v167
	v_mov_b32_e32 v219, v171
	v_mov_b32_e32 v220, v168
	v_mov_b32_e32 v221, v172
	v_pk_mul_f32 v[222:223], v[222:223], v[222:223]
	v_pk_mul_f32 v[218:219], v[218:219], v[218:219]
	v_pk_fma_f32 v[220:221], v[220:221], v[220:221], v[222:223]
	v_mov_b32_e32 v222, v166
	v_mov_b32_e32 v223, v170
	v_pk_fma_f32 v[218:219], v[222:223], v[222:223], v[218:219]
	v_mov_b32_e32 v199, v204
	v_pk_add_f32 v[218:219], v[218:219], v[220:221]
	v_mov_b32_e32 v201, v205
	v_pk_add_f32 v[218:219], v[218:219], v[218:219] op_sel:[0,1] op_sel_hi:[1,0]
	v_mov_b32_e32 v193, v203
	v_mov_b32_e32 v219, v202
	v_pk_add_f32 v[198:199], v[198:199], v[200:201]
	v_pk_add_f32 v[192:193], v[218:219], v[192:193]
	v_mov_b32_e32 v209, v216
	v_pk_add_f32 v[192:193], v[192:193], v[198:199]
	v_mov_b32_e32 v211, v217
	v_pk_add_f32 v[192:193], v[192:193], v[192:193] op_sel:[0,1] op_sel_hi:[1,0]
	v_mov_b32_e32 v207, v215
	v_mov_b32_e32 v193, v214
	v_pk_add_f32 v[198:199], v[208:209], v[210:211]
	v_pk_add_f32 v[192:193], v[192:193], v[206:207]
	s_nop 0
	v_pk_add_f32 v[192:193], v[192:193], v[198:199]
	s_nop 0
	v_add_f32_e32 v147, v192, v193
	ds_bpermute_b32 v149, v129, v147
	v_lshl_add_u64 v[164:165], s[48:49], 0, v[164:165]
	v_lshl_add_u64 v[192:193], v[164:165], 0, v[134:135]
	v_lshl_add_u64 v[162:163], v[164:165], 0, v[162:163]
	s_waitcnt lgkmcnt(0)
	v_add_f32_e32 v147, v147, v149
	ds_bpermute_b32 v149, v133, v147
	s_waitcnt lgkmcnt(0)
	v_add_f32_e32 v147, v147, v149
	ds_bpermute_b32 v149, v137, v147
	s_waitcnt lgkmcnt(0)
	v_add_f32_e32 v147, v147, v149
	ds_bpermute_b32 v149, v139, v147
	s_waitcnt lgkmcnt(0)
	v_add_f32_e32 v147, v147, v149
	ds_bpermute_b32 v149, v141, v147
	s_waitcnt lgkmcnt(0)
	v_add_f32_e32 v147, v147, v149
	ds_bpermute_b32 v149, v143, v147
	s_waitcnt lgkmcnt(0)
	v_add_f32_e32 v147, v147, v149
	v_fmamk_f32 v147, v147, 0x3a000000, v145
	v_mul_f32_e32 v149, 0x4b800000, v147
	v_cmp_gt_f32_e32 vcc, s59, v147
	s_nop 1
	v_cndmask_b32_e32 v147, v147, v149, vcc
	v_rsq_f32_e32 v147, v147
	s_nop 0
	v_mul_f32_e32 v134, 0x45800000, v147
	v_cndmask_b32_e32 v134, v147, v134, vcc
	v_pk_mul_f32 v[166:167], v[166:167], v[134:135] op_sel_hi:[1,0]
	v_pk_mul_f32 v[168:169], v[168:169], v[134:135] op_sel_hi:[1,0]
	v_pk_mul_f32 v[186:187], v[186:187], v[134:135] op_sel_hi:[1,0]
	v_pk_fma_f32 v[24:25], v[32:33], v[166:167], v[24:25]
	v_pk_mul_f32 v[32:33], v[188:189], v[134:135] op_sel_hi:[1,0]
	v_pk_mul_f32 v[170:171], v[170:171], v[134:135] op_sel_hi:[1,0]
	v_pk_mul_f32 v[172:173], v[172:173], v[134:135] op_sel_hi:[1,0]
	v_pk_mul_f32 v[174:175], v[174:175], v[134:135] op_sel_hi:[1,0]
	v_pk_mul_f32 v[176:177], v[176:177], v[134:135] op_sel_hi:[1,0]
	v_pk_mul_f32 v[178:179], v[178:179], v[134:135] op_sel_hi:[1,0]
	v_pk_mul_f32 v[180:181], v[180:181], v[134:135] op_sel_hi:[1,0]
	v_pk_mul_f32 v[182:183], v[182:183], v[134:135] op_sel_hi:[1,0]
	v_pk_mul_f32 v[184:185], v[184:185], v[134:135] op_sel_hi:[1,0]
	v_pk_fma_f32 v[26:27], v[34:35], v[168:169], v[26:27]
	v_pk_fma_f32 v[10:11], v[54:55], v[32:33], v[10:11]
	v_pk_fma_f32 v[8:9], v[52:53], v[186:187], v[8:9]
	v_lshl_add_u64 v[32:33], v[164:165], 0, v[160:161]
	v_pk_fma_f32 v[22:23], v[38:39], v[172:173], v[22:23]
	v_pk_fma_f32 v[20:21], v[36:37], v[170:171], v[20:21]
	v_pk_fma_f32 v[18:19], v[42:43], v[176:177], v[18:19]
	v_pk_fma_f32 v[16:17], v[40:41], v[174:175], v[16:17]
	v_pk_fma_f32 v[14:15], v[46:47], v[180:181], v[14:15]
	v_pk_fma_f32 v[12:13], v[44:45], v[178:179], v[12:13]
	v_pk_fma_f32 v[30:31], v[50:51], v[184:185], v[30:31]
	v_pk_fma_f32 v[28:29], v[48:49], v[182:183], v[28:29]
	global_store_dwordx4 v[192:193], v[24:27], off
	global_store_dwordx4 v[192:193], v[20:23], off offset:1024
	global_store_dwordx4 v[192:193], v[16:19], off offset:2048
	global_store_dwordx4 v[192:193], v[12:15], off offset:3072
	global_store_dwordx4 v[162:163], v[28:31], off
	global_store_dwordx4 v[32:33], v[8:11], off
	v_pk_mul_f32 v[32:33], v[190:191], v[134:135] op_sel_hi:[1,0]
	v_pk_mul_f32 v[34:35], v[194:195], v[134:135] op_sel_hi:[1,0]
	v_pk_fma_f32 v[4:5], v[60:61], v[32:33], v[4:5]
	v_pk_fma_f32 v[6:7], v[62:63], v[34:35], v[6:7]
	v_lshl_add_u64 v[32:33], v[164:165], 0, v[158:159]
	global_store_dwordx4 v[32:33], v[4:7], off
	v_pk_mul_f32 v[32:33], v[196:197], v[134:135] op_sel_hi:[1,0]
	v_pk_mul_f32 v[34:35], v[212:213], v[134:135] op_sel_hi:[1,0]
	s_waitcnt vmcnt(23)
	v_pk_fma_f32 v[0:1], v[56:57], v[32:33], v[0:1]
	v_pk_fma_f32 v[2:3], v[58:59], v[34:35], v[2:3]
	v_lshl_add_u64 v[32:33], v[164:165], 0, v[156:157]
	global_store_dwordx4 v[32:33], v[0:3], off
	v_mov_b32_e32 v34, v25
	v_mov_b32_e32 v35, v21
	v_mov_b32_e32 v32, v24
	v_mov_b32_e32 v33, v20
	v_pk_mul_f32 v[34:35], v[34:35], v[34:35]
	v_mov_b32_e32 v36, v27
	v_mov_b32_e32 v37, v23
	v_pk_fma_f32 v[32:33], v[32:33], v[32:33], v[34:35]
	v_mov_b32_e32 v34, v26
	v_mov_b32_e32 v35, v22
	v_pk_mul_f32 v[36:37], v[36:37], v[36:37]
	v_readfirstlane_b32 s83, v237
	s_add_u32 s83, s83, s94
	s_lshl_b32 s83, s83, 3
	s_sub_u32 s84, s83, s82
	s_mov_b32 s82, s83
	s_mov_b32 s85, 0
	s_mov_b64 s[6:7], s[84:85]
	s_lshl_b64 s[28:29], s[84:85], 13
	v_lshl_add_u64 v[130:131], v[130:131], 0, s[6:7]
	v_pk_fma_f32 v[34:35], v[34:35], v[34:35], v[36:37]
	v_pk_mul_f32 v[36:37], v[16:17], v[16:17]
	v_pk_add_f32 v[32:33], v[32:33], v[34:35]
	v_pk_mul_f32 v[34:35], v[18:19], v[18:19]
	v_pk_add_f32 v[32:33], v[32:33], v[32:33] op_sel_hi:[0,1]
	v_pk_mov_b32 v[38:39], v[36:37], v[34:35] op_sel:[1,0]
	v_mov_b32_e32 v37, v35
	v_mul_f32_e32 v32, v12, v12
	v_pk_add_f32 v[34:35], v[38:39], v[36:37]
	v_pk_fma_f32 v[36:37], v[12:13], v[12:13], v[32:33] op_sel_hi:[1,1,0]
	v_mul_f32_e32 v32, v14, v14
	v_pk_add_f32 v[34:35], v[34:35], v[34:35] op_sel_hi:[0,1]
	v_pk_fma_f32 v[38:39], v[14:15], v[14:15], v[32:33] op_sel_hi:[1,1,0]
	v_mul_f32_e32 v36, v28, v28
	v_mul_f32_e32 v38, v29, v29
	v_mul_f32_e32 v34, v30, v30
	v_mul_f32_e32 v32, v31, v31
	v_pk_add_f32 v[36:37], v[36:37], v[38:39]
	v_pk_add_f32 v[32:33], v[34:35], v[32:33]
	v_pk_mul_f32 v[34:35], v[10:11], v[10:11]
	v_pk_add_f32 v[32:33], v[36:37], v[32:33]
	v_pk_mul_f32 v[36:37], v[8:9], v[8:9]
	v_pk_add_f32 v[32:33], v[32:33], v[32:33] op_sel_hi:[0,1]
	v_pk_mov_b32 v[38:39], v[36:37], v[34:35] op_sel:[1,0]
	v_mov_b32_e32 v37, v35
	v_mul_f32_e32 v32, v4, v4
	v_pk_add_f32 v[34:35], v[38:39], v[36:37]
	v_pk_fma_f32 v[36:37], v[4:5], v[4:5], v[32:33] op_sel_hi:[1,1,0]
	v_mul_f32_e32 v32, v6, v6
	v_pk_add_f32 v[34:35], v[34:35], v[34:35] op_sel_hi:[0,1]
	v_pk_fma_f32 v[38:39], v[6:7], v[6:7], v[32:33] op_sel_hi:[1,1,0]
	v_mul_f32_e32 v36, v0, v0
	v_mul_f32_e32 v38, v1, v1
	v_mul_f32_e32 v34, v2, v2
	v_mul_f32_e32 v32, v3, v3
	v_pk_add_f32 v[36:37], v[36:37], v[38:39]
	v_pk_add_f32 v[32:33], v[34:35], v[32:33]
	v_lshlrev_b64 v[34:35], 12, v[154:155]
	v_pk_add_f32 v[32:33], v[36:37], v[32:33]
	v_lshl_add_u64 v[152:153], v[152:153], 0, s[28:29]
	v_add_f32_e32 v32, v32, v33
	ds_bpermute_b32 v33, v129, v32
	s_waitcnt lgkmcnt(0)
	v_add_f32_e32 v32, v32, v33
	ds_bpermute_b32 v33, v133, v32
	s_waitcnt lgkmcnt(0)
	v_add_f32_e32 v32, v32, v33
	ds_bpermute_b32 v33, v137, v32
	s_waitcnt lgkmcnt(0)
	v_add_f32_e32 v32, v32, v33
	ds_bpermute_b32 v33, v139, v32
	s_waitcnt lgkmcnt(0)
	v_add_f32_e32 v32, v32, v33
	ds_bpermute_b32 v33, v141, v32
	s_waitcnt lgkmcnt(0)
	v_add_f32_e32 v32, v32, v33
	ds_bpermute_b32 v33, v143, v32
	s_waitcnt lgkmcnt(0)
	v_add_f32_e32 v32, v32, v33
	v_fmamk_f32 v32, v32, 0x3a000000, v145
	v_mul_f32_e32 v33, 0x4b800000, v32
	v_cmp_gt_f32_e32 vcc, s59, v32
	s_nop 1
	v_cndmask_b32_e32 v32, v32, v33, vcc
	v_rsq_f32_e32 v32, v32
	s_nop 0
	v_mul_f32_e32 v33, 0x45800000, v32
	v_cndmask_b32_e32 v32, v32, v33, vcc
	v_pk_mul_f32 v[24:25], v[24:25], v[32:33] op_sel_hi:[1,0]
	v_pk_mul_f32 v[26:27], v[26:27], v[32:33] op_sel_hi:[1,0]
	v_pk_mul_f32 v[12:13], v[12:13], v[32:33] op_sel_hi:[1,0]
	v_pk_mul_f32 v[14:15], v[14:15], v[32:33] op_sel_hi:[1,0]
	s_waitcnt vmcnt(22)
	v_pk_fma_f32 v[26:27], v[122:123], v[26:27], v[126:127]
	v_pk_fma_f32 v[24:25], v[120:121], v[24:25], v[124:125]
	s_waitcnt vmcnt(16)
	v_pk_fma_f32 v[14:15], v[98:99], v[14:15], v[102:103]
	v_pk_fma_f32 v[12:13], v[96:97], v[12:13], v[100:101]
	v_cvt_pk_bf16_f32 v24, v24, v25
	v_cvt_pk_bf16_f32 v25, v26, v27
	v_lshl_add_u64 v[26:27], v[150:151], 0, v[34:35]
	v_cvt_pk_bf16_f32 v12, v12, v13
	v_cvt_pk_bf16_f32 v13, v14, v15
	v_pk_mul_f32 v[20:21], v[20:21], v[32:33] op_sel_hi:[1,0]
	v_pk_mul_f32 v[22:23], v[22:23], v[32:33] op_sel_hi:[1,0]
	v_pk_mul_f32 v[16:17], v[16:17], v[32:33] op_sel_hi:[1,0]
	v_pk_mul_f32 v[18:19], v[18:19], v[32:33] op_sel_hi:[1,0]
	global_store_dwordx2 v[26:27], v[12:13], off offset:1536
	v_pk_mul_f32 v[12:13], v[28:29], v[32:33] op_sel_hi:[1,0]
	v_pk_mul_f32 v[14:15], v[30:31], v[32:33] op_sel_hi:[1,0]
	v_pk_mul_f32 v[8:9], v[8:9], v[32:33] op_sel_hi:[1,0]
	v_pk_mul_f32 v[10:11], v[10:11], v[32:33] op_sel_hi:[1,0]
	v_pk_mul_f32 v[4:5], v[4:5], v[32:33] op_sel_hi:[1,0]
	v_pk_mul_f32 v[6:7], v[6:7], v[32:33] op_sel_hi:[1,0]
	v_pk_mul_f32 v[0:1], v[0:1], v[32:33] op_sel_hi:[1,0]
	v_pk_mul_f32 v[2:3], v[2:3], v[32:33] op_sel_hi:[1,0]
	v_pk_fma_f32 v[22:23], v[114:115], v[22:23], v[118:119]
	v_pk_fma_f32 v[20:21], v[112:113], v[20:21], v[116:117]
	v_pk_fma_f32 v[18:19], v[106:107], v[18:19], v[110:111]
	v_pk_fma_f32 v[16:17], v[104:105], v[16:17], v[108:109]
	s_waitcnt vmcnt(15)
	v_pk_fma_f32 v[14:15], v[90:91], v[14:15], v[94:95]
	v_pk_fma_f32 v[12:13], v[88:89], v[12:13], v[92:93]
	s_waitcnt vmcnt(13)
	v_pk_fma_f32 v[10:11], v[82:83], v[10:11], v[86:87]
	v_pk_fma_f32 v[8:9], v[80:81], v[8:9], v[84:85]
	s_waitcnt vmcnt(11)
	v_pk_fma_f32 v[6:7], v[74:75], v[6:7], v[78:79]
	v_pk_fma_f32 v[4:5], v[72:73], v[4:5], v[76:77]
	s_waitcnt vmcnt(9)
	v_pk_fma_f32 v[2:3], v[66:67], v[2:3], v[70:71]
	v_pk_fma_f32 v[0:1], v[64:65], v[0:1], v[68:69]
	v_cmp_lt_i32_e32 vcc, s60, v130
	v_cvt_pk_bf16_f32 v20, v20, v21
	v_cvt_pk_bf16_f32 v21, v22, v23
	v_cvt_pk_bf16_f32 v16, v16, v17
	v_cvt_pk_bf16_f32 v17, v18, v19
	v_cvt_pk_bf16_f32 v12, v12, v13
	v_cvt_pk_bf16_f32 v13, v14, v15
	v_cvt_pk_bf16_f32 v8, v8, v9
	v_cvt_pk_bf16_f32 v9, v10, v11
	v_cvt_pk_bf16_f32 v4, v4, v5
	v_cvt_pk_bf16_f32 v5, v6, v7
	v_cvt_pk_bf16_f32 v0, v0, v1
	v_cvt_pk_bf16_f32 v1, v2, v3
	s_or_b64 s[30:31], vcc, s[30:31]
	global_store_dwordx2 v[26:27], v[24:25], off
	global_store_dwordx2 v[26:27], v[20:21], off offset:512
	global_store_dwordx2 v[26:27], v[16:17], off offset:1024
	global_store_dwordx2 v[26:27], v[12:13], off offset:2048
	global_store_dwordx2 v[26:27], v[8:9], off offset:2560
	global_store_dwordx2 v[26:27], v[4:5], off offset:3072
	global_store_dwordx2 v[26:27], v[0:1], off offset:3584
	s_andn2_b64 exec, exec, s[30:31]
	s_cbranch_execz .LBB0_742
.LBB0_738:
	s_mov_b64 s[80:81], exec
	s_mov_b64 exec, 1
	v_mov_b32_e32 v237, 1
	global_atomic_add v237, v236, v237, s[50:51] sc0
	s_mov_b64 exec, s[80:81]
	v_cmp_gt_i32_e32 vcc, s33, v130
	v_cmp_lt_i32_e64 s[4:5], s35, v130
	v_add_u32_e32 v134, 0xffffe000, v130
	s_and_saveexec_b64 s[62:63], s[4:5]
	s_xor_b64 s[4:5], exec, s[62:63]
	v_lshlrev_b64 v[0:1], 13, v[134:135]
	v_mov_b32_e32 v154, v130
	v_mov_b32_e32 v155, v135
	v_lshl_add_u64 v[0:1], s[18:19], 0, v[0:1]
	v_lshlrev_b64 v[164:165], 13, v[154:155]
	s_andn2_saveexec_b64 s[4:5], s[4:5]
	s_cbranch_execz .LBB0_737
	v_lshl_add_u64 v[0:1], s[16:17], 0, v[152:153]
	v_mov_b64_e32 v[164:165], v[152:153]
	v_mov_b64_e32 v[154:155], v[130:131]
	s_branch .LBB0_737
